# retention per-chunk output: 4 flat dwordx2 row-per-lane stores -> 2 global dwordx4 via v_permlane32_swap, role wait vmcnt(5)->(3) (on v46)
# speedup vs baseline: 1.0095x; 1.0095x over previous
; #define LAS __attribute__((address_space(3)))
; __device__ __forceinline__ int lane_id_asm() { int l; asm volatile("v_mbcnt_lo_u32_b32 %0, -1, 0\n\tv_mbcnt_hi_u32_b32 %0, -1, %0" : "=v"(l)); return l; }
; __device__ __forceinline__ void ret_mfma(const Params& P, LAS unsigned char* lds, int wave) {
;     ...
;     const int lane = lane_id_asm(), t = wave * 64 + lane, q32 = lane & 31, hf = lane >> 5, i16 = lane & 15, blk = (lane >> 4) & 1;
;     const int trrow = 8 * hf + (i16 >> 2), trcol = (16 * blk + 4 * (i16 & 3)) * 2;
;     for (int unit = blockIdx.x; unit < 256; unit += gridDim.x) {
;         const int xcd_ = unit & 7, idx_ = unit >> 3, bh = xcd_ * 4 + (idx_ >> 3), slice = idx_ & 7, b = bh >> 2, hh = bh & 3;
;         const float gam = 1.f - exp2f(-5.f - (float)hh), lg = log2f(gam), g64 = exp2f(lg * 64.f);
;         for (int i = t; i < 33792 / 16; i += NTHREADS) *(LAS u32x4*)(lds + ST_OFF + i * 16) = (u32x4){0u, 0u, 0u, 0u};
;         f32x16 st[2];
; #pragma unroll
;         for (int a = 0; a < 2; ++a)
; #pragma unroll
;             for (int i = 0; i < 16; ++i) st[a][i] = 0.f;
;         const size_t rb = (size_t)b * SEQ;
;         float dec[16];
;         { const int mblk = (wave & 3) >> 1, nblk = wave & 1, n = nblk * 32 + q32;
; #pragma unroll
;           for (int i = 0; i < 16; ++i) { const int mm = mblk * 32 + 8 * (i >> 2) + 4 * hf + (i & 3); const int dist = n > mm ? n - mm : mm - n;
;               dec[i] = wave < 4 ? __builtin_amdgcn_exp2f(lg * (float)(dist - (63 - mm))) : __builtin_amdgcn_exp2f(lg * (float)(n + 1)); } }
;         u32x4 pq[4], pkk[4], pvv;
;         const int vr = t >> 3, vc = t & 7;
; #pragma unroll
;         for (int i = 0; i < 4; ++i) { const int id = t + 512 * i, r = id >> 5, ch = id & 31;
;             pq[i] = *(const u32x4*)(QK + (rb + r) * 2048 + hh * 256 + ch * 8); pkk[i] = *(const u32x4*)(QK + (rb + r) * 2048 + 1024 + hh * 256 + ch * 8); }
;         pvv = *(const u32x4*)(V + (rb + vr) * 2048 + hh * 512 + slice * 64 + vc * 8);
.LBB0_246:
	s_or_b64 exec, exec, s[50:51]
	s_add_u32 s60, s54, 0x1f000000
	s_addc_u32 s61, s55, 0
	s_cmpk_gt_i32 s2, 0xff
	s_waitcnt lgkmcnt(0)
	s_barrier
	v_mbcnt_lo_u32_b32 v0, -1, 0
	v_mbcnt_hi_u32_b32 v0, -1, v0
	s_cbranch_scc1 .LBB0_270
	v_ashrrev_i32_e32 v3, 5, v0
	v_and_b32_e32 v8, 31, v0
	v_readlane_b32 s4, v254, 4
	s_cmpk_lt_u32 s3, 0x100
	v_lshlrev_b32_e32 v5, 3, v3
	v_lshrrev_b32_e32 v2, 2, v0
	v_and_or_b32 v84, s4, 32, v8
	s_cselect_b64 s[4:5], -1, 0
	s_cmpk_gt_u32 s3, 0xff
	v_add_u32_e32 v1, s64, v0
	v_and_or_b32 v6, v2, 3, v5
	v_lshlrev_b32_e32 v2, 2, v0
	v_and_b32_e32 v4, 16, v0
	s_cselect_b64 s[10:11], -1, 0
	s_lshl_b32 s6, s33, 4
	v_and_or_b32 v2, v2, 12, v4
	s_and_b32 s6, s6, 32
	v_lshlrev_b32_e32 v86, 2, v3
	v_ashrrev_i32_e32 v88, 3, v1
	s_movk_i32 s9, 0xc0
	v_lshlrev_b32_e32 v7, 1, v2
	v_add_u32_e32 v9, s6, v86
	v_mul_lo_u32 v13, v88, s9
	s_add_i32 s6, 0, 0x10800
	v_add_u32_e32 v13, s6, v13
	v_add_u32_e32 v148, s6, v7
	s_add_i32 s6, s64, 0
	s_add_i32 s16, 0, 0x16800
	s_add_i32 s7, 0, 0x1ec00
	v_add_u32_e32 v7, s6, v7
	s_add_i32 s6, s16, s64
	v_lshlrev_b32_e32 v149, 4, v3
	v_mul_u32_u24_e32 v15, 0x210, v84
	v_lshl_add_u32 v14, v8, 1, s6
	v_add3_u32 v150, 0, v15, v149
	s_movk_i32 s6, 0x90
	v_mov_b32_e32 v15, s7
	v_add_u32_e32 v2, 1, v84
	v_mad_u32_u24 v151, v84, s6, v15
	s_add_i32 s6, s33, -4
	v_cvt_f32_ubyte0_e32 v85, v2
	v_and_b32_e32 v10, 7, v0
	v_lshlrev_b32_e32 v2, 3, v0
	v_lshlrev_b32_e32 v11, 4, v0
	s_lshr_b32 s14, s6, 1
	v_cmp_lt_u32_e64 s[6:7], 31, v0
	v_sub_u32_e32 v0, v84, v9
	v_sub_u32_e32 v16, 0, v0
	v_max_i32_e32 v16, v0, v16
	s_movk_i32 s21, 0xffc1
	v_add3_u32 v16, v9, v16, s21
	v_cvt_f32_i32_e32 v152, v16
	v_xad_u32 v16, v9, -1, v84
	v_sub_u32_e32 v17, 0, v16
	v_max_i32_e32 v16, v16, v17
	s_movk_i32 s21, 0xffc2
	v_add3_u32 v16, v9, v16, s21
	v_cvt_f32_i32_e32 v153, v16
	v_add_u32_e32 v16, -2, v0
	v_sub_u32_e32 v17, 2, v0
	v_max_i32_e32 v16, v16, v17
	s_movk_i32 s21, 0xffc3
	v_add3_u32 v16, v9, v16, s21
	v_cvt_f32_i32_e32 v154, v16
	v_add_u32_e32 v16, -3, v0
	v_sub_u32_e32 v17, 3, v0
	v_max_i32_e32 v16, v16, v17
	s_movk_i32 s21, 0xffc4
	v_add3_u32 v16, v9, v16, s21
	v_cvt_f32_i32_e32 v155, v16
	v_add_u32_e32 v16, -8, v0
	v_sub_u32_e32 v17, 8, v0
	v_max_i32_e32 v16, v16, v17
	s_movk_i32 s21, 0xffc9
	v_add3_u32 v16, v9, v16, s21
	v_cvt_f32_i32_e32 v156, v16
	v_add_u32_e32 v16, -9, v0
	v_sub_u32_e32 v17, 9, v0
	v_max_i32_e32 v16, v16, v17
	s_movk_i32 s21, 0xffca
	v_add3_u32 v16, v9, v16, s21
	v_cvt_f32_i32_e32 v157, v16
	v_add_u32_e32 v16, -10, v0
	v_sub_u32_e32 v17, 10, v0
	v_max_i32_e32 v16, v16, v17
	s_movk_i32 s21, 0xffcb
	v_add3_u32 v16, v9, v16, s21
	v_cvt_f32_i32_e32 v158, v16
	v_add_u32_e32 v16, -11, v0
	v_sub_u32_e32 v17, 11, v0
	v_max_i32_e32 v16, v16, v17
	s_movk_i32 s21, 0xffcc
	v_add3_u32 v16, v9, v16, s21
	v_cvt_f32_i32_e32 v159, v16
	v_add_u32_e32 v16, -16, v0
	v_sub_u32_e32 v17, 16, v0
	v_max_i32_e32 v16, v16, v17
	s_movk_i32 s21, 0xffd1
	v_add3_u32 v16, v9, v16, s21
	v_cvt_f32_i32_e32 v160, v16
	v_subrev_u32_e32 v16, 17, v0
	v_sub_u32_e32 v17, 17, v0
	v_max_i32_e32 v16, v16, v17
	s_movk_i32 s21, 0xffd2
	v_add3_u32 v16, v9, v16, s21
	v_cvt_f32_i32_e32 v161, v16
	v_subrev_u32_e32 v16, 18, v0
	v_sub_u32_e32 v17, 18, v0
	v_max_i32_e32 v16, v16, v17
	s_movk_i32 s21, 0xffd3
	v_add3_u32 v16, v9, v16, s21
	v_cvt_f32_i32_e32 v162, v16
	v_subrev_u32_e32 v16, 19, v0
	v_sub_u32_e32 v17, 19, v0
	v_max_i32_e32 v16, v16, v17
	s_movk_i32 s21, 0xffd4
	v_add3_u32 v16, v9, v16, s21
	v_cvt_f32_i32_e32 v163, v16
	v_subrev_u32_e32 v16, 24, v0
	v_sub_u32_e32 v17, 24, v0
	v_max_i32_e32 v16, v16, v17
	s_movk_i32 s21, 0xffd9
	v_add3_u32 v16, v9, v16, s21
	v_cvt_f32_i32_e32 v164, v16
	v_subrev_u32_e32 v16, 25, v0
	v_sub_u32_e32 v17, 25, v0
	v_max_i32_e32 v16, v16, v17
	s_movk_i32 s21, 0xffda
	v_add3_u32 v16, v9, v16, s21
	v_cvt_f32_i32_e32 v165, v16
	v_subrev_u32_e32 v16, 26, v0
	v_sub_u32_e32 v17, 26, v0
	v_max_i32_e32 v16, v16, v17
	s_movk_i32 s21, 0xffdb
	v_add3_u32 v16, v9, v16, s21
	v_cvt_f32_i32_e32 v166, v16
	v_subrev_u32_e32 v16, 27, v0
	v_sub_u32_e32 v0, 27, v0
	v_max_i32_e32 v0, v16, v0
	s_movk_i32 s21, 0xffdc
	v_add3_u32 v0, v9, v0, s21
	s_movk_i32 s8, 0x840
	s_lshr_b32 s18, s3, 7
	v_cvt_f32_i32_e32 v167, v0
	v_add_u32_e32 v0, 0x200, v1
	v_cmp_gt_i32_e64 s[0:1], s8, v1
	v_ashrrev_i32_e32 v94, 5, v0
	v_add_u32_e32 v0, 0x400, v1
	v_mul_lo_u32 v3, v3, s8
	s_mul_i32 s8, s18, 0x4200
	s_movk_i32 s17, 0x210
	v_ashrrev_i32_e32 v92, 5, v1
	v_ashrrev_i32_e32 v96, 5, v0
	v_add_u32_e32 v0, 0x600, v1
	v_add_u32_e32 v169, 0xfffffe00, v1
	v_mov_b32_e32 v1, s8
	v_and_b32_e32 v2, 0xf8, v2
	v_and_b32_e32 v12, 0x1f0, v11
	v_ashrrev_i32_e32 v98, 5, v0
	v_mad_u32_u24 v1, v8, s17, v1
	s_mov_b32 s15, 0
	v_mov_b32_e32 v91, 0
	v_lshlrev_b32_e32 v4, 3, v10
	v_add_u32_e32 v12, 0, v12
	v_lshlrev_b32_e32 v10, 4, v10
	s_lshl_b32 s19, s18, 6
	v_add_u32_e32 v5, v151, v5
	v_lshl_add_u32 v15, s14, 6, v148
	s_lshl_b32 s20, s14, 5
	v_mul_lo_u32 v0, v92, s17
	v_mul_lo_u32 v9, v94, s17
	v_mul_lo_u32 v16, v96, s17
	v_mul_lo_u32 v17, v98, s17
	v_mul_lo_u32 v168, v6, s9
	v_mul_lo_u32 v6, v6, s17
	v_lshlrev_b32_e32 v90, 1, v2
	s_add_i32 s16, s16, s68
	v_add3_u32 v1, v1, v149, 0
	v_ashrrev_i32_e32 v89, 31, v88
	v_ashrrev_i32_e32 v87, 31, v86
	v_ashrrev_i32_e32 v93, 31, v92
	v_ashrrev_i32_e32 v95, 31, v94
	v_ashrrev_i32_e32 v97, 31, v96
	v_ashrrev_i32_e32 v99, 31, v98
	v_lshl_add_u64 v[100:101], s[44:45], 0, v[90:91]
	v_add_u32_e32 v170, s16, v11
	v_add_u32_e32 v171, 0xe400, v1
	v_add_u32_e32 v172, 0x8400, v1
	s_movk_i32 s24, 0x63f
	s_mov_b32 s25, 0xc2fc0000
	s_mov_b32 s26, 0x800000
	v_lshlrev_b32_e32 v90, 1, v2
	v_lshlrev_b32_e32 v102, 1, v4
	s_lshl_b64 s[16:17], s[14:15], 2
	s_lshl_b32 s27, s20, 1
	v_add_u32_e32 v173, v12, v0
	v_add_u32_e32 v174, v12, v9
	v_add_u32_e32 v175, v12, v16
	v_add_u32_e32 v176, v12, v17
	v_add_u32_e32 v177, v13, v10
	v_add_u32_e32 v178, s19, v5
	v_add_u32_e32 v179, v7, v6
	v_add_u32_e32 v180, v14, v3
	v_add_u32_e32 v181, v15, v168
	v_mov_b32_e32 v186, v91
	v_mov_b32_e32 v187, v91
	v_mov_b32_e32 v188, v91
	v_mov_b32_e32 v189, v91
	v_mov_b32_e32 v182, 0x42800000
	v_mov_b32_e32 v183, 0x42000000
	v_mbcnt_hi_u32_b32 v184, -1, v244
	v_and_b32_e32 v142, 32, v184
	v_mov_b32_e32 v143, 0
	v_lshrrev_b32_e32 v142, 2, v142
	v_and_b32_e32 v242, 31, v184
	v_mul_u32_u24_e32 v242, 0x210, v242
	v_lshrrev_b32_e32 v103, 5, v184
	v_lshl_add_u32 v242, v103, 3, v242
	v_add_u32_e32 v242, s64, v242
	v_add_u32_e32 v242, 0x16800, v242
	s_mov_b32 s28, s2
	s_branch .LBB0_249

; __device__ __forceinline__ unsigned cvt_pk_bf16(float lo, float hi) { f32x2 v = {lo, hi}; bf16x2_t b = __builtin_convertvector(v, bf16x2_t); return __builtin_bit_cast(unsigned, b); }
; __device__ __forceinline__ void ret_mfma(const Params& P, LAS unsigned char* lds, int wave) {
;     ...
;                 bf16_t* op = V + (r0 + n) * 2048 + hh * 512 + slice * 64 + dvblk * 32 + 4 * hf;
; #pragma unroll
;                 for (int j = 0; j < 4; ++j) { u32x2 w; w.x = cvt_pk_bf16(acc[4 * j], acc[4 * j + 1]); w.y = cvt_pk_bf16(acc[4 * j + 2], acc[4 * j + 3]); *(u32x2*)(op + 8 * j) = w; }
.LBB0_253:
	s_or_b64 exec, exec, s[8:9]
	v_lshlrev_b64 v[146:147], 12, v[146:147]
	v_lshl_add_u64 v[146:147], v[128:129], 0, v[146:147]
	v_cvt_pk_bf16_f32 v32, v32, v33
	v_cvt_pk_bf16_f32 v33, v34, v35
	v_cvt_pk_bf16_f32 v34, v36, v37
	v_cvt_pk_bf16_f32 v35, v38, v39
	v_cvt_pk_bf16_f32 v36, v40, v41
	v_cvt_pk_bf16_f32 v37, v42, v43
	v_cvt_pk_bf16_f32 v38, v44, v45
	v_cvt_pk_bf16_f32 v39, v46, v47
	v_lshl_add_u64 v[146:147], v[146:147], 0, v[142:143]
	v_permlane32_swap_b32_e32 v32, v34
	v_permlane32_swap_b32_e32 v33, v35
	v_permlane32_swap_b32_e32 v36, v38
	v_permlane32_swap_b32_e32 v37, v39
	global_store_dwordx4 v[146:147], v[32:35], off
	global_store_dwordx4 v[146:147], v[36:39], off offset:32

; #define LAS __attribute__((address_space(3)))
; __device__ __forceinline__ void ret_mfma(const Params& P, LAS unsigned char* lds, int wave) {
;     ...
;         for (int c = 0; c < 64; ++c) {
; #pragma unroll
;             for (int i = 0; i < 4; ++i) { const int id = t + 512 * i, r = id >> 5, ch = id & 31;
;                 *(LAS u32x4*)(lds + Q_OFF + r * QP + ch * 16) = pq[i]; *(LAS u32x4*)(lds + K_OFF + r * QP + ch * 16) = pkk[i]; }
;             *(LAS u32x4*)(lds + V_OFF + vr * VP + vc * 16) = pvv;
;             __syncthreads();
;             if (c + 1 < 64) { const size_t r1 = rb + (size_t)(c + 1) * 64;
; #pragma unroll
;                 for (int i = 0; i < 4; ++i) { const int id = t + 512 * i, r = id >> 5, ch = id & 31;
;                     pq[i] = *(const u32x4*)(QK + (r1 + r) * 2048 + hh * 256 + ch * 8); pkk[i] = *(const u32x4*)(QK + (r1 + r) * 2048 + 1024 + hh * 256 + ch * 8); }
;                 pvv = *(const u32x4*)(V + (r1 + vr) * 2048 + hh * 512 + slice * 64 + vc * 8); }
.LBB0_255:
	s_add_i32 s14, s29, 1
	s_cmp_lg_u32 s29, 63
	s_waitcnt lgkmcnt(0)
	ds_write_b128 v173, v[48:51]
	ds_write_b128 v173, v[52:55] offset:33792
	ds_write_b128 v174, v[56:59]
	ds_write_b128 v174, v[60:63] offset:33792
	ds_write_b128 v175, v[64:67]
	ds_write_b128 v175, v[68:71] offset:33792
	ds_write_b128 v176, v[72:75]
	ds_write_b128 v176, v[76:79] offset:33792
	ds_write_b128 v177, v[80:83]
	s_waitcnt lgkmcnt(0)
	s_barrier
	s_andn2_b64 vcc, exec, s[10:11]
	s_cbranch_vccnz .Lret_wait_lo
	s_waitcnt vmcnt(3)
	s_branch .Lret_wait_done
